# attention finish blocks (dec+ctx): 15 parameter/gate loads issued together into their own registers, waits recounted; on top of v138
# speedup vs baseline: 1.0128x; 1.0058x over previous
.LBB0_482:
	v_lshlrev_b32_e32 v0, 1, v122
	v_lshl_add_u64 v[4:5], v[118:119], 0, v[0:1]
	v_lshlrev_b32_e32 v0, 3, v131
	v_lshl_add_u64 v[4:5], v[4:5], 0, v[0:1]
	v_add_co_u32_e32 v6, vcc, s87, v4
	v_mov_b32_e32 v11, v2
	s_nop 0
	v_addc_co_u32_e32 v7, vcc, 0, v5, vcc
	global_load_dwordx2 v[6:7], v[6:7], off offset:2048
	v_cmp_lt_i32_e32 vcc, v207, v206
	v_add_f32_e32 v10, v159, v163
	v_add_f32_e32 v12, v160, v161
	v_cndmask_b32_e32 v3, v205, v207, vcc
	v_mov_b32_e32 v13, v100
	v_lshlrev_b32_e32 v3, 2, v3
	v_permlane16_swap_b32_e32 v2, v11
	v_permlane16_swap_b32_e32 v100, v13
	ds_bpermute_b32 v14, v3, v10
	ds_bpermute_b32 v15, v3, v12
	v_add_f32_e32 v16, v2, v11
	v_lshlrev_b32_e32 v84, 4, v131
	v_add_f32_e32 v131, v100, v13
	v_mov_b32_e32 v13, v16
	s_nop 1
	v_permlane32_swap_b32_e32 v16, v13
	s_mov_b64 s[0:1], 0x1800
	v_add_f32_e32 v13, v16, v13
	v_lshl_add_u64 v[2:3], v[4:5], 0, s[0:1]
	v_div_scale_f32 v16, s[0:1], v13, v13, 1.0
	s_waitcnt lgkmcnt(0)
	v_add_f32_e32 v4, v10, v14
	v_add_f32_e32 v5, v12, v15
	v_rcp_f32_e32 v12, v16
	v_mul_f32_e32 v4, 0x3fb8aa3b, v4
	v_mul_f32_e32 v5, 0x3fb8aa3b, v5
	v_exp_f32_e32 v4, v4
	v_exp_f32_e32 v5, v5
	v_fma_f32 v10, -v16, v12, 1.0
	v_mov_b32_e32 v11, v131
	v_div_scale_f32 v14, vcc, 1.0, v13, 1.0
	v_fmac_f32_e32 v12, v10, v12
	v_permlane32_swap_b32_e32 v131, v11
	v_sub_f32_e32 v10, v4, v5
	v_mul_f32_e32 v15, v14, v12
	v_pk_add_f32 v[4:5], v[130:131], v[10:11]
	v_fma_f32 v10, -v16, v15, v14
	v_fmac_f32_e32 v15, v10, v12
	v_div_scale_f32 v10, s[0:1], v5, v5, v4
	v_fma_f32 v14, -v16, v15, v14
	v_rcp_f32_e32 v16, v10
	v_div_fmas_f32 v12, v14, v12, v15
	v_div_fixup_f32 v14, v12, v13, 1.0
	v_div_scale_f32 v11, s[0:1], v4, v5, v4
	v_fma_f32 v12, -v10, v16, 1.0
	v_fmac_f32_e32 v16, v12, v16
	v_mul_f32_e32 v12, v11, v16
	v_fma_f32 v13, -v10, v12, v11
	v_fmac_f32_e32 v12, v13, v16
	v_fma_f32 v10, -v10, v12, v11
	s_mov_b64 vcc, s[0:1]
	v_div_fmas_f32 v10, v10, v16, v12
	v_div_fixup_f32 v86, v10, v5, v4
	v_pk_mul_f32 v[4:5], v[78:79], v[86:87] op_sel_hi:[1,0]
	v_pk_mul_f32 v[10:11], v[76:77], v[86:87] op_sel_hi:[1,0]
	global_load_dwordx4 v[164:167], v84, s[56:57]
	global_load_dwordx2 v[196:197], v[2:3], off offset:32
	global_load_dwordx4 v[168:171], v84, s[56:57] offset:64
	global_load_dwordx2 v[198:199], v[2:3], off offset:64
	global_load_dwordx4 v[172:175], v84, s[56:57] offset:128
	global_load_dwordx2 v[208:209], v[2:3], off offset:96
	global_load_dwordx4 v[176:179], v84, s[56:57] offset:192
	global_load_dwordx2 v[210:211], v[2:3], off offset:128
	global_load_dwordx4 v[180:183], v84, s[56:57] offset:256
	global_load_dwordx2 v[212:213], v[2:3], off offset:160
	global_load_dwordx4 v[184:187], v84, s[56:57] offset:320
	global_load_dwordx2 v[214:215], v[2:3], off offset:192
	global_load_dwordx4 v[188:191], v84, s[56:57] offset:384
	global_load_dwordx2 v[226:227], v[2:3], off offset:224
	global_load_dwordx4 v[192:195], v84, s[56:57] offset:448
	v_pk_fma_f32 v[80:81], v[80:81], v[14:15], v[10:11] op_sel_hi:[1,0,1] neg_lo:[0,0,1] neg_hi:[0,0,1]
	v_pk_fma_f32 v[82:83], v[82:83], v[14:15], v[4:5] op_sel_hi:[1,0,1] neg_lo:[0,0,1] neg_hi:[0,0,1]
	v_mul_f32_e32 v4, v81, v81
	v_pk_fma_f32 v[4:5], v[80:81], v[80:81], v[4:5] op_sel_hi:[1,1,0]
	v_lshlrev_b32_e32 v92, 22, v123
	v_pk_fma_f32 v[4:5], v[82:83], v[82:83], v[4:5]
	v_mov_b32_e32 v93, v1
	v_lshlrev_b64 v[8:9], 6, v[116:117]
	s_mov_b32 s0, 0xc073000
	s_waitcnt vmcnt(13)
	v_lshlrev_b32_e32 v10, 16, v6
	v_and_b32_e32 v11, 0xffff0000, v6
	v_lshlrev_b32_e32 v6, 16, v7
	v_and_b32_e32 v7, 0xffff0000, v7
	v_mul_f32_e32 v15, 0xbfb8aa3b, v6
	v_mul_f32_e32 v16, 0xbfb8aa3b, v7
	v_mul_f32_e32 v12, 0xbfb8aa3b, v10
	v_mul_f32_e32 v13, 0xbfb8aa3b, v11
	v_exp_f32_e32 v15, v15
	v_exp_f32_e32 v16, v16
	v_exp_f32_e32 v12, v12
	v_exp_f32_e32 v13, v13
	v_add_f32_e32 v15, 1.0, v15
	v_add_f32_e32 v17, 1.0, v16
	v_add_f32_e32 v12, 1.0, v12
	v_add_f32_e32 v13, 1.0, v13
	v_rcp_f32_e32 v16, v15
	v_rcp_f32_e32 v17, v17
	v_rcp_f32_e32 v12, v12
	v_rcp_f32_e32 v13, v13
	v_pk_mul_f32 v[90:91], v[16:17], v[6:7]
	v_pk_mul_f32 v[6:7], v[70:71], v[86:87] op_sel_hi:[1,0]
	v_pk_mul_f32 v[88:89], v[12:13], v[10:11]
	v_mul_f32_e32 v10, v83, v83
	v_pk_fma_f32 v[70:71], v[74:75], v[14:15], v[6:7] op_sel_hi:[1,0,1] neg_lo:[0,0,1] neg_hi:[0,0,1]
	v_pk_mul_f32 v[6:7], v[68:69], v[86:87] op_sel_hi:[1,0]
	v_pk_add_f32 v[4:5], v[10:11], v[4:5] op_sel_hi:[0,1]
	v_pk_fma_f32 v[68:69], v[72:73], v[14:15], v[6:7] op_sel_hi:[1,0,1] neg_lo:[0,0,1] neg_hi:[0,0,1]
	s_nop 0
	v_pk_fma_f32 v[4:5], v[68:69], v[68:69], v[4:5]
	v_mul_f32_e32 v6, v69, v69
	v_pk_add_f32 v[4:5], v[6:7], v[4:5] op_sel_hi:[0,1]
	v_pk_fma_f32 v[4:5], v[70:71], v[70:71], v[4:5]
	v_mul_f32_e32 v6, v71, v71
	v_pk_add_f32 v[4:5], v[6:7], v[4:5] op_sel_hi:[0,1]
	v_pk_mul_f32 v[6:7], v[62:63], v[86:87] op_sel_hi:[1,0]
	s_nop 0
	v_pk_fma_f32 v[16:17], v[66:67], v[14:15], v[6:7] op_sel_hi:[1,0,1] neg_lo:[0,0,1] neg_hi:[0,0,1]
	v_pk_mul_f32 v[6:7], v[60:61], v[86:87] op_sel_hi:[1,0]
	s_nop 0
	v_pk_fma_f32 v[60:61], v[64:65], v[14:15], v[6:7] op_sel_hi:[1,0,1] neg_lo:[0,0,1] neg_hi:[0,0,1]
	s_nop 0
	v_pk_fma_f32 v[4:5], v[60:61], v[60:61], v[4:5]
	v_mul_f32_e32 v6, v61, v61
	v_pk_add_f32 v[4:5], v[6:7], v[4:5] op_sel_hi:[0,1]
	v_pk_fma_f32 v[4:5], v[16:17], v[16:17], v[4:5]
	v_mul_f32_e32 v6, v17, v17
	v_pk_add_f32 v[4:5], v[6:7], v[4:5] op_sel_hi:[0,1]
	v_pk_mul_f32 v[6:7], v[54:55], v[86:87] op_sel_hi:[1,0]
	s_nop 0
	v_pk_fma_f32 v[54:55], v[58:59], v[14:15], v[6:7] op_sel_hi:[1,0,1] neg_lo:[0,0,1] neg_hi:[0,0,1]
	v_pk_mul_f32 v[6:7], v[52:53], v[86:87] op_sel_hi:[1,0]
	s_nop 0
	v_pk_fma_f32 v[52:53], v[56:57], v[14:15], v[6:7] op_sel_hi:[1,0,1] neg_lo:[0,0,1] neg_hi:[0,0,1]
	s_nop 0
	v_pk_fma_f32 v[4:5], v[52:53], v[52:53], v[4:5]
	v_mul_f32_e32 v6, v53, v53
	v_pk_add_f32 v[4:5], v[6:7], v[4:5] op_sel_hi:[0,1]
	v_pk_fma_f32 v[4:5], v[54:55], v[54:55], v[4:5]
	v_mul_f32_e32 v6, v55, v55
	v_pk_add_f32 v[4:5], v[6:7], v[4:5] op_sel_hi:[0,1]
	v_pk_mul_f32 v[6:7], v[46:47], v[86:87] op_sel_hi:[1,0]
	s_nop 0
	v_pk_fma_f32 v[46:47], v[50:51], v[14:15], v[6:7] op_sel_hi:[1,0,1] neg_lo:[0,0,1] neg_hi:[0,0,1]
	v_pk_mul_f32 v[6:7], v[44:45], v[86:87] op_sel_hi:[1,0]
	s_nop 0
	v_pk_fma_f32 v[44:45], v[48:49], v[14:15], v[6:7] op_sel_hi:[1,0,1] neg_lo:[0,0,1] neg_hi:[0,0,1]
	s_nop 0
	v_pk_fma_f32 v[4:5], v[44:45], v[44:45], v[4:5]
	v_mul_f32_e32 v6, v45, v45
	v_pk_add_f32 v[4:5], v[6:7], v[4:5] op_sel_hi:[0,1]
	v_pk_fma_f32 v[4:5], v[46:47], v[46:47], v[4:5]
	v_mul_f32_e32 v6, v47, v47
	v_pk_add_f32 v[4:5], v[6:7], v[4:5] op_sel_hi:[0,1]
	v_pk_mul_f32 v[6:7], v[38:39], v[86:87] op_sel_hi:[1,0]
	s_nop 0
	v_pk_fma_f32 v[18:19], v[42:43], v[14:15], v[6:7] op_sel_hi:[1,0,1] neg_lo:[0,0,1] neg_hi:[0,0,1]
	v_pk_mul_f32 v[6:7], v[36:37], v[86:87] op_sel_hi:[1,0]
	s_nop 0
	v_pk_fma_f32 v[36:37], v[40:41], v[14:15], v[6:7] op_sel_hi:[1,0,1] neg_lo:[0,0,1] neg_hi:[0,0,1]
	s_nop 0
	v_pk_fma_f32 v[4:5], v[36:37], v[36:37], v[4:5]
	v_mul_f32_e32 v6, v37, v37
	v_pk_add_f32 v[4:5], v[6:7], v[4:5] op_sel_hi:[0,1]
	v_pk_fma_f32 v[4:5], v[18:19], v[18:19], v[4:5]
	v_mul_f32_e32 v6, v19, v19
	v_pk_add_f32 v[4:5], v[6:7], v[4:5] op_sel_hi:[0,1]
	v_pk_mul_f32 v[6:7], v[22:23], v[86:87] op_sel_hi:[1,0]
	s_nop 0
	v_pk_fma_f32 v[10:11], v[34:35], v[14:15], v[6:7] op_sel_hi:[1,0,1] neg_lo:[0,0,1] neg_hi:[0,0,1]
	v_pk_mul_f32 v[6:7], v[20:21], v[86:87] op_sel_hi:[1,0]
	s_nop 0
	v_pk_fma_f32 v[12:13], v[32:33], v[14:15], v[6:7] op_sel_hi:[1,0,1] neg_lo:[0,0,1] neg_hi:[0,0,1]
	s_nop 0
	v_pk_fma_f32 v[4:5], v[12:13], v[12:13], v[4:5]
	v_mul_f32_e32 v6, v13, v13
	v_pk_add_f32 v[4:5], v[6:7], v[4:5] op_sel_hi:[0,1]
	v_pk_fma_f32 v[4:5], v[10:11], v[10:11], v[4:5]
	v_mul_f32_e32 v6, v11, v11
	v_pk_add_f32 v[20:21], v[6:7], v[4:5] op_sel_hi:[0,1]
	v_pk_mul_f32 v[6:7], v[28:29], v[86:87] op_sel_hi:[1,0]
	v_pk_mul_f32 v[4:5], v[30:31], v[86:87] op_sel_hi:[1,0]
	v_pk_fma_f32 v[6:7], v[24:25], v[14:15], v[6:7] op_sel_hi:[1,0,1] neg_lo:[0,0,1] neg_hi:[0,0,1]
	v_pk_fma_f32 v[4:5], v[26:27], v[14:15], v[4:5] op_sel_hi:[1,0,1] neg_lo:[0,0,1] neg_hi:[0,0,1]
	v_pk_fma_f32 v[14:15], v[6:7], v[6:7], v[20:21]
	v_mul_f32_e32 v20, v7, v7
	v_pk_add_f32 v[14:15], v[20:21], v[14:15] op_sel_hi:[0,1]
	v_pk_fma_f32 v[14:15], v[4:5], v[4:5], v[14:15]
	v_mul_f32_e32 v20, v5, v5
	v_pk_add_f32 v[14:15], v[20:21], v[14:15] op_sel_hi:[0,1]
	v_mov_b32_e32 v15, v14
	s_nop 1
	v_permlane16_swap_b32_e32 v14, v15
	v_add_f32_e32 v14, v14, v15
	v_mov_b32_e32 v15, v14
	s_nop 1
	v_permlane32_swap_b32_e32 v14, v15
	v_add_f32_e32 v14, v14, v15
	v_fmamk_f32 v14, v14, 0x3c000000, v201
	v_mul_f32_e32 v15, 0x4b800000, v14
	v_cmp_gt_f32_e32 vcc, s40, v14
	v_lshlrev_b32_e32 v26, 16, v196
	v_and_b32_e32 v27, 0xffff0000, v196
	v_cndmask_b32_e32 v14, v14, v15, vcc
	v_rsq_f32_e32 v20, v14
	v_lshl_add_u64 v[14:15], s[22:23], 0, v[92:93]
	v_lshl_add_u64 v[14:15], v[14:15], 0, v[8:9]
	v_lshl_add_u64 v[24:25], v[14:15], 0, v[0:1]
	v_mul_f32_e32 v8, 0x45800000, v20
	v_cndmask_b32_e32 v8, v20, v8, vcc
	v_mul_f32_e32 v8, v151, v8
	v_pk_mul_f32 v[20:21], v[80:81], v[8:9] op_sel_hi:[1,0]
	v_pk_mul_f32 v[22:23], v[82:83], v[8:9] op_sel_hi:[1,0]
	v_pk_mul_f32 v[20:21], v[164:165], v[20:21]
	v_pk_mul_f32 v[22:23], v[166:167], v[22:23]
	v_pk_mul_f32 v[20:21], v[88:89], v[20:21]
	v_pk_mul_f32 v[22:23], v[90:91], v[22:23]
	v_cvt_pk_bf16_f32 v20, v20, v21
	v_cvt_pk_bf16_f32 v21, v22, v23
	v_add_co_u32_e32 v22, vcc, s0, v24
	v_mul_f32_e32 v9, 0xbfb8aa3b, v26
	s_nop 0
	v_addc_co_u32_e32 v23, vcc, 0, v25, vcc
	global_store_dwordx2 v[22:23], v[20:21], off
	v_exp_f32_e32 v9, v9
	v_mul_f32_e32 v28, 0xbfb8aa3b, v27
	v_exp_f32_e32 v29, v28
	v_lshlrev_b32_e32 v30, 16, v197
	v_add_f32_e32 v9, 1.0, v9
	v_rcp_f32_e32 v28, v9
	v_add_f32_e32 v9, 1.0, v29
	v_rcp_f32_e32 v29, v9
	v_and_b32_e32 v31, 0xffff0000, v197
	v_mul_f32_e32 v9, 0xbfb8aa3b, v30
	v_exp_f32_e32 v9, v9
	v_mul_f32_e32 v32, 0xbfb8aa3b, v31
	v_exp_f32_e32 v35, v32
	v_add_f32_e32 v9, 1.0, v9
	v_rcp_f32_e32 v34, v9
	v_add_f32_e32 v9, 1.0, v35
	v_rcp_f32_e32 v35, v9
	v_pk_mul_f32 v[26:27], v[28:29], v[26:27]
	s_mov_b64 s[0:1], 0xc073000
	v_lshl_add_u64 v[24:25], v[24:25], 0, s[0:1]
	v_pk_mul_f32 v[28:29], v[34:35], v[30:31]
	v_pk_mul_f32 v[30:31], v[68:69], v[8:9] op_sel_hi:[1,0]
	s_mov_b64 s[0:1], 0xc173000
	s_waitcnt vmcnt(13)
	v_pk_mul_f32 v[20:21], v[168:169], v[30:31]
	s_nop 0
	v_pk_mul_f32 v[20:21], v[20:21], v[26:27]
	v_pk_mul_f32 v[26:27], v[70:71], v[8:9] op_sel_hi:[1,0]
	v_cvt_pk_bf16_f32 v20, v20, v21
	v_pk_mul_f32 v[22:23], v[170:171], v[26:27]
	s_waitcnt vmcnt(12)
	v_lshlrev_b32_e32 v30, 16, v198
	v_pk_mul_f32 v[22:23], v[22:23], v[28:29]
	v_pk_mul_f32 v[28:29], v[60:61], v[8:9] op_sel_hi:[1,0]
	v_cvt_pk_bf16_f32 v21, v22, v23
	global_store_dwordx2 v[24:25], v[20:21], off offset:32
	v_and_b32_e32 v31, 0xffff0000, v198
	v_mul_f32_e32 v9, 0xbfb8aa3b, v30
	v_mul_f32_e32 v34, 0xbfb8aa3b, v31
	v_exp_f32_e32 v9, v9
	v_exp_f32_e32 v38, v34
	v_lshlrev_b32_e32 v32, 16, v199
	v_and_b32_e32 v33, 0xffff0000, v199
	v_add_f32_e32 v9, 1.0, v9
	v_mul_f32_e32 v40, 0xbfb8aa3b, v32
	v_add_f32_e32 v39, 1.0, v38
	v_rcp_f32_e32 v38, v9
	v_mul_f32_e32 v9, 0xbfb8aa3b, v33
	v_exp_f32_e32 v40, v40
	v_exp_f32_e32 v9, v9
	v_rcp_f32_e32 v39, v39
	v_lshl_add_u64 v[24:25], v[14:15], 0, s[0:1]
	v_add_f32_e32 v9, 1.0, v9
	v_pk_mul_f32 v[16:17], v[16:17], v[8:9] op_sel_hi:[1,0]
	v_pk_mul_f32 v[30:31], v[38:39], v[30:31]
	v_lshl_add_u64 v[26:27], v[24:25], 0, v[0:1]
	s_mov_b64 s[0:1], 0xc273000
	s_waitcnt vmcnt(12)
	v_pk_mul_f32 v[20:21], v[172:173], v[28:29]
	v_add_f32_e32 v28, 1.0, v40
	v_rcp_f32_e32 v28, v28
	v_rcp_f32_e32 v29, v9
	v_pk_mul_f32 v[16:17], v[174:175], v[16:17]
	v_pk_mul_f32 v[20:21], v[20:21], v[30:31]
	v_pk_mul_f32 v[22:23], v[28:29], v[32:33]
	s_nop 0
	v_pk_mul_f32 v[16:17], v[16:17], v[22:23]
	v_cvt_pk_bf16_f32 v20, v20, v21
	v_cvt_pk_bf16_f32 v21, v16, v17
	global_store_dwordx2 v[26:27], v[20:21], off
	v_mov_b32_e32 v17, v1
	v_or_b32_e32 v16, 32, v0
	s_waitcnt vmcnt(12)
	v_lshlrev_b32_e32 v26, 16, v208
	v_and_b32_e32 v27, 0xffff0000, v208
	v_lshlrev_b32_e32 v28, 16, v209
	v_and_b32_e32 v29, 0xffff0000, v209
	v_mul_f32_e32 v9, 0xbfb8aa3b, v26
	v_mul_f32_e32 v30, 0xbfb8aa3b, v27
	v_mul_f32_e32 v31, 0xbfb8aa3b, v28
	v_mul_f32_e32 v32, 0xbfb8aa3b, v29
	v_exp_f32_e32 v9, v9
	v_exp_f32_e32 v30, v30
	v_exp_f32_e32 v31, v31
	v_exp_f32_e32 v32, v32
	v_add_f32_e32 v9, 1.0, v9
	v_add_f32_e32 v33, 1.0, v30
	v_add_f32_e32 v34, 1.0, v31
	v_add_f32_e32 v35, 1.0, v32
	v_rcp_f32_e32 v30, v9
	v_rcp_f32_e32 v31, v33
	v_rcp_f32_e32 v32, v34
	v_rcp_f32_e32 v33, v35
	v_pk_mul_f32 v[34:35], v[52:53], v[8:9] op_sel_hi:[1,0]
	v_pk_mul_f32 v[38:39], v[54:55], v[8:9] op_sel_hi:[1,0]
	v_pk_mul_f32 v[26:27], v[30:31], v[26:27]
	v_pk_mul_f32 v[28:29], v[32:33], v[28:29]
	v_lshl_add_u64 v[24:25], v[24:25], 0, v[16:17]
	v_pk_mul_f32 v[30:31], v[44:45], v[8:9] op_sel_hi:[1,0]
	v_pk_mul_f32 v[32:33], v[46:47], v[8:9] op_sel_hi:[1,0]
	s_waitcnt vmcnt(11)
	v_pk_mul_f32 v[20:21], v[176:177], v[34:35]
	v_pk_mul_f32 v[22:23], v[178:179], v[38:39]
	v_pk_mul_f32 v[20:21], v[20:21], v[26:27]
	v_pk_mul_f32 v[22:23], v[22:23], v[28:29]
	v_cvt_pk_bf16_f32 v20, v20, v21
	v_cvt_pk_bf16_f32 v21, v22, v23
	global_store_dwordx2 v[24:25], v[20:21], off
	s_nop 0
	v_lshl_add_u64 v[26:27], v[14:15], 0, s[0:1]
	v_lshl_add_u64 v[28:29], v[26:27], 0, v[0:1]
	s_mov_b64 s[0:1], 0xc373000
	v_lshl_add_u64 v[14:15], v[14:15], 0, s[0:1]
	s_waitcnt vmcnt(11)
	v_lshlrev_b32_e32 v38, 16, v210
	v_and_b32_e32 v39, 0xffff0000, v210
	v_lshlrev_b32_e32 v24, 16, v211
	v_and_b32_e32 v25, 0xffff0000, v211
	v_mul_f32_e32 v9, 0xbfb8aa3b, v38
	v_mul_f32_e32 v40, 0xbfb8aa3b, v39
	v_mul_f32_e32 v41, 0xbfb8aa3b, v24
	v_mul_f32_e32 v42, 0xbfb8aa3b, v25
	v_exp_f32_e32 v9, v9
	v_exp_f32_e32 v40, v40
	v_exp_f32_e32 v41, v41
	v_exp_f32_e32 v42, v42
	v_add_f32_e32 v9, 1.0, v9
	v_add_f32_e32 v43, 1.0, v40
	v_add_f32_e32 v44, 1.0, v41
	v_add_f32_e32 v45, 1.0, v42
	v_rcp_f32_e32 v40, v9
	v_rcp_f32_e32 v41, v43
	v_rcp_f32_e32 v42, v44
	v_rcp_f32_e32 v43, v45
	s_waitcnt vmcnt(10)
	v_pk_mul_f32 v[20:21], v[30:31], v[180:181]
	v_pk_mul_f32 v[22:23], v[32:33], v[182:183]
	v_pk_mul_f32 v[30:31], v[40:41], v[38:39]
	v_pk_mul_f32 v[24:25], v[42:43], v[24:25]
	v_pk_mul_f32 v[20:21], v[20:21], v[30:31]
	v_pk_mul_f32 v[22:23], v[22:23], v[24:25]
	v_cvt_pk_bf16_f32 v20, v20, v21
	v_cvt_pk_bf16_f32 v21, v22, v23
	global_store_dwordx2 v[28:29], v[20:21], off
	v_lshl_add_u64 v[24:25], v[26:27], 0, v[16:17]
	s_waitcnt vmcnt(10)
	v_lshlrev_b32_e32 v26, 16, v212
	v_and_b32_e32 v27, 0xffff0000, v212
	v_lshlrev_b32_e32 v28, 16, v213
	v_and_b32_e32 v29, 0xffff0000, v213
	v_mul_f32_e32 v9, 0xbfb8aa3b, v26
	v_mul_f32_e32 v30, 0xbfb8aa3b, v27
	v_mul_f32_e32 v31, 0xbfb8aa3b, v28
	v_mul_f32_e32 v32, 0xbfb8aa3b, v29
	v_exp_f32_e32 v9, v9
	v_exp_f32_e32 v30, v30
	v_exp_f32_e32 v31, v31
	v_exp_f32_e32 v32, v32
	v_add_f32_e32 v9, 1.0, v9
	v_add_f32_e32 v33, 1.0, v30
	v_add_f32_e32 v34, 1.0, v31
	v_add_f32_e32 v35, 1.0, v32
	v_rcp_f32_e32 v30, v9
	v_rcp_f32_e32 v31, v33
	v_rcp_f32_e32 v32, v34
	v_rcp_f32_e32 v33, v35
	v_pk_mul_f32 v[34:35], v[36:37], v[8:9] op_sel_hi:[1,0]
	v_pk_mul_f32 v[18:19], v[18:19], v[8:9] op_sel_hi:[1,0]
	v_pk_mul_f32 v[26:27], v[30:31], v[26:27]
	v_pk_mul_f32 v[28:29], v[32:33], v[28:29]
	v_pk_mul_f32 v[12:13], v[12:13], v[8:9] op_sel_hi:[1,0]
	v_pk_mul_f32 v[10:11], v[10:11], v[8:9] op_sel_hi:[1,0]
	s_waitcnt vmcnt(9)
	v_pk_mul_f32 v[20:21], v[34:35], v[184:185]
	v_pk_mul_f32 v[18:19], v[18:19], v[186:187]
	v_pk_mul_f32 v[20:21], v[20:21], v[26:27]
	v_pk_mul_f32 v[18:19], v[18:19], v[28:29]
	v_cvt_pk_bf16_f32 v20, v20, v21
	v_cvt_pk_bf16_f32 v21, v18, v19
	global_store_dwordx2 v[24:25], v[20:21], off
	s_nop 0
	v_lshl_add_u64 v[24:25], v[14:15], 0, v[0:1]
	s_waitcnt vmcnt(9)
	v_lshlrev_b32_e32 v26, 16, v214
	v_and_b32_e32 v27, 0xffff0000, v214
	v_lshlrev_b32_e32 v22, 16, v215
	v_and_b32_e32 v23, 0xffff0000, v215
	v_mul_f32_e32 v0, 0xbfb8aa3b, v26
	v_mul_f32_e32 v9, 0xbfb8aa3b, v27
	v_mul_f32_e32 v28, 0xbfb8aa3b, v22
	v_mul_f32_e32 v29, 0xbfb8aa3b, v23
	v_exp_f32_e32 v0, v0
	v_exp_f32_e32 v9, v9
	v_exp_f32_e32 v28, v28
	v_exp_f32_e32 v29, v29
	v_add_f32_e32 v0, 1.0, v0
	v_add_f32_e32 v9, 1.0, v9
	v_add_f32_e32 v30, 1.0, v28
	v_add_f32_e32 v31, 1.0, v29
	v_rcp_f32_e32 v28, v0
	v_rcp_f32_e32 v29, v9
	v_rcp_f32_e32 v30, v30
	v_rcp_f32_e32 v31, v31
	s_waitcnt vmcnt(8)
	v_pk_mul_f32 v[12:13], v[12:13], v[188:189]
	v_pk_mul_f32 v[10:11], v[10:11], v[190:191]
	v_pk_mul_f32 v[18:19], v[28:29], v[26:27]
	v_pk_mul_f32 v[20:21], v[30:31], v[22:23]
	v_pk_mul_f32 v[12:13], v[12:13], v[18:19]
	v_pk_mul_f32 v[10:11], v[10:11], v[20:21]
	v_cvt_pk_bf16_f32 v12, v12, v13
	v_cvt_pk_bf16_f32 v13, v10, v11
	global_store_dwordx2 v[24:25], v[12:13], off
	s_waitcnt vmcnt(8)
	v_lshlrev_b32_e32 v18, 16, v226
	v_and_b32_e32 v19, 0xffff0000, v226
	v_lshlrev_b32_e32 v2, 16, v227
	v_and_b32_e32 v3, 0xffff0000, v227
	v_mul_f32_e32 v0, 0xbfb8aa3b, v18
	v_mul_f32_e32 v9, 0xbfb8aa3b, v19
	v_mul_f32_e32 v20, 0xbfb8aa3b, v2
	v_mul_f32_e32 v21, 0xbfb8aa3b, v3
	v_exp_f32_e32 v0, v0
	v_exp_f32_e32 v9, v9
	v_exp_f32_e32 v20, v20
	v_exp_f32_e32 v21, v21
	v_add_f32_e32 v0, 1.0, v0
	v_add_f32_e32 v9, 1.0, v9
	v_add_f32_e32 v22, 1.0, v20
	v_add_f32_e32 v23, 1.0, v21
	v_rcp_f32_e32 v20, v0
	v_rcp_f32_e32 v21, v9
	v_rcp_f32_e32 v22, v22
	v_rcp_f32_e32 v23, v23
	v_pk_mul_f32 v[6:7], v[6:7], v[8:9] op_sel_hi:[1,0]
	v_pk_mul_f32 v[4:5], v[4:5], v[8:9] op_sel_hi:[1,0]
	v_pk_mul_f32 v[8:9], v[20:21], v[18:19]
	v_pk_mul_f32 v[2:3], v[22:23], v[2:3]
	s_waitcnt vmcnt(7)
	v_pk_mul_f32 v[6:7], v[6:7], v[192:193]
	v_pk_mul_f32 v[4:5], v[4:5], v[194:195]
	v_pk_mul_f32 v[6:7], v[6:7], v[8:9]
	v_pk_mul_f32 v[2:3], v[4:5], v[2:3]
	v_cvt_pk_bf16_f32 v4, v6, v7
	v_cvt_pk_bf16_f32 v5, v2, v3
	v_lshl_add_u64 v[2:3], v[14:15], 0, v[16:17]
	global_store_dwordx2 v[2:3], v[4:5], off

.LBB0_519:
	v_lshlrev_b32_e32 v0, 1, v118
	v_lshl_add_u64 v[4:5], v[120:121], 0, v[0:1]
	v_lshlrev_b32_e32 v0, 3, v131
	v_lshl_add_u64 v[4:5], v[4:5], 0, v[0:1]
	v_add_co_u32_e32 v6, vcc, s87, v4
	v_mov_b32_e32 v11, v2
	s_nop 0
	v_addc_co_u32_e32 v7, vcc, 0, v5, vcc
	global_load_dwordx2 v[6:7], v[6:7], off offset:2048
	v_cmp_lt_i32_e32 vcc, v207, v206
	v_add_f32_e32 v10, v142, v143
	v_add_f32_e32 v12, v140, v141
	v_cndmask_b32_e32 v3, v205, v207, vcc
	v_mov_b32_e32 v13, v100
	v_lshlrev_b32_e32 v3, 2, v3
	v_permlane16_swap_b32_e32 v2, v11
	v_permlane16_swap_b32_e32 v100, v13
	ds_bpermute_b32 v14, v3, v10
	ds_bpermute_b32 v15, v3, v12
	v_add_f32_e32 v16, v2, v11
	v_lshlrev_b32_e32 v84, 4, v131
	v_add_f32_e32 v131, v100, v13
	v_mov_b32_e32 v13, v16
	s_nop 1
	v_permlane32_swap_b32_e32 v16, v13
	s_mov_b64 s[0:1], 0x1800
	v_add_f32_e32 v13, v16, v13
	v_lshl_add_u64 v[2:3], v[4:5], 0, s[0:1]
	v_div_scale_f32 v16, s[0:1], v13, v13, 1.0
	s_waitcnt lgkmcnt(0)
	v_add_f32_e32 v4, v10, v14
	v_add_f32_e32 v5, v12, v15
	v_rcp_f32_e32 v12, v16
	v_mul_f32_e32 v4, 0x3fb8aa3b, v4
	v_mul_f32_e32 v5, 0x3fb8aa3b, v5
	v_exp_f32_e32 v4, v4
	v_exp_f32_e32 v5, v5
	v_fma_f32 v10, -v16, v12, 1.0
	v_mov_b32_e32 v11, v131
	v_div_scale_f32 v14, vcc, 1.0, v13, 1.0
	v_fmac_f32_e32 v12, v10, v12
	v_permlane32_swap_b32_e32 v131, v11
	v_sub_f32_e32 v10, v4, v5
	v_mul_f32_e32 v15, v14, v12
	v_pk_add_f32 v[4:5], v[130:131], v[10:11]
	v_fma_f32 v10, -v16, v15, v14
	v_fmac_f32_e32 v15, v10, v12
	v_div_scale_f32 v10, s[0:1], v5, v5, v4
	v_fma_f32 v14, -v16, v15, v14
	v_rcp_f32_e32 v16, v10
	v_div_fmas_f32 v12, v14, v12, v15
	v_div_fixup_f32 v14, v12, v13, 1.0
	v_div_scale_f32 v11, s[0:1], v4, v5, v4
	v_fma_f32 v12, -v10, v16, 1.0
	v_fmac_f32_e32 v16, v12, v16
	v_mul_f32_e32 v12, v11, v16
	v_fma_f32 v13, -v10, v12, v11
	v_fmac_f32_e32 v12, v13, v16
	v_fma_f32 v10, -v10, v12, v11
	s_mov_b64 vcc, s[0:1]
	v_div_fmas_f32 v10, v10, v16, v12
	v_div_fixup_f32 v86, v10, v5, v4
	v_pk_mul_f32 v[4:5], v[78:79], v[86:87] op_sel_hi:[1,0]
	v_pk_mul_f32 v[10:11], v[76:77], v[86:87] op_sel_hi:[1,0]
	global_load_dwordx4 v[164:167], v84, s[56:57]
	global_load_dwordx2 v[196:197], v[2:3], off offset:32
	global_load_dwordx4 v[168:171], v84, s[56:57] offset:64
	global_load_dwordx2 v[198:199], v[2:3], off offset:64
	global_load_dwordx4 v[172:175], v84, s[56:57] offset:128
	global_load_dwordx2 v[208:209], v[2:3], off offset:96
	global_load_dwordx4 v[176:179], v84, s[56:57] offset:192
	global_load_dwordx2 v[210:211], v[2:3], off offset:128
	global_load_dwordx4 v[180:183], v84, s[56:57] offset:256
	global_load_dwordx2 v[212:213], v[2:3], off offset:160
	global_load_dwordx4 v[184:187], v84, s[56:57] offset:320
	global_load_dwordx2 v[214:215], v[2:3], off offset:192
	global_load_dwordx4 v[188:191], v84, s[56:57] offset:384
	global_load_dwordx2 v[226:227], v[2:3], off offset:224
	global_load_dwordx4 v[192:195], v84, s[56:57] offset:448
	v_pk_fma_f32 v[80:81], v[80:81], v[14:15], v[10:11] op_sel_hi:[1,0,1] neg_lo:[0,0,1] neg_hi:[0,0,1]
	v_pk_fma_f32 v[82:83], v[82:83], v[14:15], v[4:5] op_sel_hi:[1,0,1] neg_lo:[0,0,1] neg_hi:[0,0,1]
	v_mul_f32_e32 v4, v81, v81
	v_pk_fma_f32 v[4:5], v[80:81], v[80:81], v[4:5] op_sel_hi:[1,1,0]
	v_lshlrev_b32_e32 v92, 22, v119
	v_pk_fma_f32 v[4:5], v[82:83], v[82:83], v[4:5]
	v_mov_b32_e32 v93, v1
	v_lshlrev_b64 v[8:9], 6, v[116:117]
	s_mov_b32 s0, 0xc073000
	s_waitcnt vmcnt(13)
	v_lshlrev_b32_e32 v10, 16, v6
	v_and_b32_e32 v11, 0xffff0000, v6
	v_lshlrev_b32_e32 v6, 16, v7
	v_and_b32_e32 v7, 0xffff0000, v7
	v_mul_f32_e32 v15, 0xbfb8aa3b, v6
	v_mul_f32_e32 v16, 0xbfb8aa3b, v7
	v_mul_f32_e32 v12, 0xbfb8aa3b, v10
	v_mul_f32_e32 v13, 0xbfb8aa3b, v11
	v_exp_f32_e32 v15, v15
	v_exp_f32_e32 v16, v16
	v_exp_f32_e32 v12, v12
	v_exp_f32_e32 v13, v13
	v_add_f32_e32 v15, 1.0, v15
	v_add_f32_e32 v17, 1.0, v16
	v_add_f32_e32 v12, 1.0, v12
	v_add_f32_e32 v13, 1.0, v13
	v_rcp_f32_e32 v16, v15
	v_rcp_f32_e32 v17, v17
	v_rcp_f32_e32 v12, v12
	v_rcp_f32_e32 v13, v13
	v_pk_mul_f32 v[90:91], v[16:17], v[6:7]
	v_pk_mul_f32 v[6:7], v[70:71], v[86:87] op_sel_hi:[1,0]
	v_pk_mul_f32 v[88:89], v[12:13], v[10:11]
	v_mul_f32_e32 v10, v83, v83
	v_pk_fma_f32 v[70:71], v[74:75], v[14:15], v[6:7] op_sel_hi:[1,0,1] neg_lo:[0,0,1] neg_hi:[0,0,1]
	v_pk_mul_f32 v[6:7], v[68:69], v[86:87] op_sel_hi:[1,0]
	v_pk_add_f32 v[4:5], v[10:11], v[4:5] op_sel_hi:[0,1]
	v_pk_fma_f32 v[68:69], v[72:73], v[14:15], v[6:7] op_sel_hi:[1,0,1] neg_lo:[0,0,1] neg_hi:[0,0,1]
	s_nop 0
	v_pk_fma_f32 v[4:5], v[68:69], v[68:69], v[4:5]
	v_mul_f32_e32 v6, v69, v69
	v_pk_add_f32 v[4:5], v[6:7], v[4:5] op_sel_hi:[0,1]
	v_pk_fma_f32 v[4:5], v[70:71], v[70:71], v[4:5]
	v_mul_f32_e32 v6, v71, v71
	v_pk_add_f32 v[4:5], v[6:7], v[4:5] op_sel_hi:[0,1]
	v_pk_mul_f32 v[6:7], v[62:63], v[86:87] op_sel_hi:[1,0]
	s_nop 0
	v_pk_fma_f32 v[16:17], v[66:67], v[14:15], v[6:7] op_sel_hi:[1,0,1] neg_lo:[0,0,1] neg_hi:[0,0,1]
	v_pk_mul_f32 v[6:7], v[60:61], v[86:87] op_sel_hi:[1,0]
	s_nop 0
	v_pk_fma_f32 v[60:61], v[64:65], v[14:15], v[6:7] op_sel_hi:[1,0,1] neg_lo:[0,0,1] neg_hi:[0,0,1]
	s_nop 0
	v_pk_fma_f32 v[4:5], v[60:61], v[60:61], v[4:5]
	v_mul_f32_e32 v6, v61, v61
	v_pk_add_f32 v[4:5], v[6:7], v[4:5] op_sel_hi:[0,1]
	v_pk_fma_f32 v[4:5], v[16:17], v[16:17], v[4:5]
	v_mul_f32_e32 v6, v17, v17
	v_pk_add_f32 v[4:5], v[6:7], v[4:5] op_sel_hi:[0,1]
	v_pk_mul_f32 v[6:7], v[54:55], v[86:87] op_sel_hi:[1,0]
	s_nop 0
	v_pk_fma_f32 v[54:55], v[58:59], v[14:15], v[6:7] op_sel_hi:[1,0,1] neg_lo:[0,0,1] neg_hi:[0,0,1]
	v_pk_mul_f32 v[6:7], v[52:53], v[86:87] op_sel_hi:[1,0]
	s_nop 0
	v_pk_fma_f32 v[52:53], v[56:57], v[14:15], v[6:7] op_sel_hi:[1,0,1] neg_lo:[0,0,1] neg_hi:[0,0,1]
	s_nop 0
	v_pk_fma_f32 v[4:5], v[52:53], v[52:53], v[4:5]
	v_mul_f32_e32 v6, v53, v53
	v_pk_add_f32 v[4:5], v[6:7], v[4:5] op_sel_hi:[0,1]
	v_pk_fma_f32 v[4:5], v[54:55], v[54:55], v[4:5]
	v_mul_f32_e32 v6, v55, v55
	v_pk_add_f32 v[4:5], v[6:7], v[4:5] op_sel_hi:[0,1]
	v_pk_mul_f32 v[6:7], v[46:47], v[86:87] op_sel_hi:[1,0]
	s_nop 0
	v_pk_fma_f32 v[46:47], v[50:51], v[14:15], v[6:7] op_sel_hi:[1,0,1] neg_lo:[0,0,1] neg_hi:[0,0,1]
	v_pk_mul_f32 v[6:7], v[44:45], v[86:87] op_sel_hi:[1,0]
	s_nop 0
	v_pk_fma_f32 v[44:45], v[48:49], v[14:15], v[6:7] op_sel_hi:[1,0,1] neg_lo:[0,0,1] neg_hi:[0,0,1]
	s_nop 0
	v_pk_fma_f32 v[4:5], v[44:45], v[44:45], v[4:5]
	v_mul_f32_e32 v6, v45, v45
	v_pk_add_f32 v[4:5], v[6:7], v[4:5] op_sel_hi:[0,1]
	v_pk_fma_f32 v[4:5], v[46:47], v[46:47], v[4:5]
	v_mul_f32_e32 v6, v47, v47
	v_pk_add_f32 v[4:5], v[6:7], v[4:5] op_sel_hi:[0,1]
	v_pk_mul_f32 v[6:7], v[38:39], v[86:87] op_sel_hi:[1,0]
	s_nop 0
	v_pk_fma_f32 v[18:19], v[42:43], v[14:15], v[6:7] op_sel_hi:[1,0,1] neg_lo:[0,0,1] neg_hi:[0,0,1]
	v_pk_mul_f32 v[6:7], v[36:37], v[86:87] op_sel_hi:[1,0]
	s_nop 0
	v_pk_fma_f32 v[36:37], v[40:41], v[14:15], v[6:7] op_sel_hi:[1,0,1] neg_lo:[0,0,1] neg_hi:[0,0,1]
	s_nop 0
	v_pk_fma_f32 v[4:5], v[36:37], v[36:37], v[4:5]
	v_mul_f32_e32 v6, v37, v37
	v_pk_add_f32 v[4:5], v[6:7], v[4:5] op_sel_hi:[0,1]
	v_pk_fma_f32 v[4:5], v[18:19], v[18:19], v[4:5]
	v_mul_f32_e32 v6, v19, v19
	v_pk_add_f32 v[4:5], v[6:7], v[4:5] op_sel_hi:[0,1]
	v_pk_mul_f32 v[6:7], v[22:23], v[86:87] op_sel_hi:[1,0]
	s_nop 0
	v_pk_fma_f32 v[10:11], v[34:35], v[14:15], v[6:7] op_sel_hi:[1,0,1] neg_lo:[0,0,1] neg_hi:[0,0,1]
	v_pk_mul_f32 v[6:7], v[20:21], v[86:87] op_sel_hi:[1,0]
	s_nop 0
	v_pk_fma_f32 v[12:13], v[32:33], v[14:15], v[6:7] op_sel_hi:[1,0,1] neg_lo:[0,0,1] neg_hi:[0,0,1]
	s_nop 0
	v_pk_fma_f32 v[4:5], v[12:13], v[12:13], v[4:5]
	v_mul_f32_e32 v6, v13, v13
	v_pk_add_f32 v[4:5], v[6:7], v[4:5] op_sel_hi:[0,1]
	v_pk_fma_f32 v[4:5], v[10:11], v[10:11], v[4:5]
	v_mul_f32_e32 v6, v11, v11
	v_pk_add_f32 v[20:21], v[6:7], v[4:5] op_sel_hi:[0,1]
	v_pk_mul_f32 v[6:7], v[28:29], v[86:87] op_sel_hi:[1,0]
	v_pk_mul_f32 v[4:5], v[30:31], v[86:87] op_sel_hi:[1,0]
	v_pk_fma_f32 v[6:7], v[24:25], v[14:15], v[6:7] op_sel_hi:[1,0,1] neg_lo:[0,0,1] neg_hi:[0,0,1]
	v_pk_fma_f32 v[4:5], v[26:27], v[14:15], v[4:5] op_sel_hi:[1,0,1] neg_lo:[0,0,1] neg_hi:[0,0,1]
	v_pk_fma_f32 v[14:15], v[6:7], v[6:7], v[20:21]
	v_mul_f32_e32 v20, v7, v7
	v_pk_add_f32 v[14:15], v[20:21], v[14:15] op_sel_hi:[0,1]
	v_pk_fma_f32 v[14:15], v[4:5], v[4:5], v[14:15]
	v_mul_f32_e32 v20, v5, v5
	v_pk_add_f32 v[14:15], v[20:21], v[14:15] op_sel_hi:[0,1]
	v_mov_b32_e32 v15, v14
	s_nop 1
	v_permlane16_swap_b32_e32 v14, v15
	v_add_f32_e32 v14, v14, v15
	v_mov_b32_e32 v15, v14
	s_nop 1
	v_permlane32_swap_b32_e32 v14, v15
	v_add_f32_e32 v14, v14, v15
	v_fmamk_f32 v14, v14, 0x3c000000, v201
	v_mul_f32_e32 v15, 0x4b800000, v14
	v_cmp_gt_f32_e32 vcc, s40, v14
	v_lshlrev_b32_e32 v26, 16, v196
	v_and_b32_e32 v27, 0xffff0000, v196
	v_cndmask_b32_e32 v14, v14, v15, vcc
	v_rsq_f32_e32 v20, v14
	v_lshl_add_u64 v[14:15], s[22:23], 0, v[92:93]
	v_lshl_add_u64 v[14:15], v[14:15], 0, v[8:9]
	v_lshl_add_u64 v[24:25], v[14:15], 0, v[0:1]
	v_mul_f32_e32 v8, 0x45800000, v20
	v_cndmask_b32_e32 v8, v20, v8, vcc
	v_mul_f32_e32 v8, v151, v8
	v_pk_mul_f32 v[20:21], v[80:81], v[8:9] op_sel_hi:[1,0]
	v_pk_mul_f32 v[22:23], v[82:83], v[8:9] op_sel_hi:[1,0]
	v_pk_mul_f32 v[20:21], v[164:165], v[20:21]
	v_pk_mul_f32 v[22:23], v[166:167], v[22:23]
	v_pk_mul_f32 v[20:21], v[88:89], v[20:21]
	v_pk_mul_f32 v[22:23], v[90:91], v[22:23]
	v_cvt_pk_bf16_f32 v20, v20, v21
	v_cvt_pk_bf16_f32 v21, v22, v23
	v_add_co_u32_e32 v22, vcc, s0, v24
	v_mul_f32_e32 v9, 0xbfb8aa3b, v26
	s_nop 0
	v_addc_co_u32_e32 v23, vcc, 0, v25, vcc
	global_store_dwordx2 v[22:23], v[20:21], off
	v_exp_f32_e32 v9, v9
	v_mul_f32_e32 v28, 0xbfb8aa3b, v27
	v_exp_f32_e32 v29, v28
	v_lshlrev_b32_e32 v30, 16, v197
	v_add_f32_e32 v9, 1.0, v9
	v_rcp_f32_e32 v28, v9
	v_add_f32_e32 v9, 1.0, v29
	v_rcp_f32_e32 v29, v9
	v_and_b32_e32 v31, 0xffff0000, v197
	v_mul_f32_e32 v9, 0xbfb8aa3b, v30
	v_exp_f32_e32 v9, v9
	v_mul_f32_e32 v32, 0xbfb8aa3b, v31
	v_exp_f32_e32 v35, v32
	v_add_f32_e32 v9, 1.0, v9
	v_rcp_f32_e32 v34, v9
	v_add_f32_e32 v9, 1.0, v35
	v_rcp_f32_e32 v35, v9
	v_pk_mul_f32 v[26:27], v[28:29], v[26:27]
	s_mov_b64 s[0:1], 0xc073000
	v_lshl_add_u64 v[24:25], v[24:25], 0, s[0:1]
	v_pk_mul_f32 v[28:29], v[34:35], v[30:31]
	v_pk_mul_f32 v[30:31], v[68:69], v[8:9] op_sel_hi:[1,0]
	s_mov_b64 s[0:1], 0xc173000
	s_waitcnt vmcnt(13)
	v_pk_mul_f32 v[20:21], v[168:169], v[30:31]
	s_nop 0
	v_pk_mul_f32 v[20:21], v[20:21], v[26:27]
	v_pk_mul_f32 v[26:27], v[70:71], v[8:9] op_sel_hi:[1,0]
	v_cvt_pk_bf16_f32 v20, v20, v21
	v_pk_mul_f32 v[22:23], v[170:171], v[26:27]
	s_waitcnt vmcnt(12)
	v_lshlrev_b32_e32 v30, 16, v198
	v_pk_mul_f32 v[22:23], v[22:23], v[28:29]
	v_pk_mul_f32 v[28:29], v[60:61], v[8:9] op_sel_hi:[1,0]
	v_cvt_pk_bf16_f32 v21, v22, v23
	global_store_dwordx2 v[24:25], v[20:21], off offset:32
	v_and_b32_e32 v31, 0xffff0000, v198
	v_mul_f32_e32 v9, 0xbfb8aa3b, v30
	v_mul_f32_e32 v34, 0xbfb8aa3b, v31
	v_exp_f32_e32 v9, v9
	v_exp_f32_e32 v38, v34
	v_lshlrev_b32_e32 v32, 16, v199
	v_and_b32_e32 v33, 0xffff0000, v199
	v_add_f32_e32 v9, 1.0, v9
	v_mul_f32_e32 v40, 0xbfb8aa3b, v32
	v_add_f32_e32 v39, 1.0, v38
	v_rcp_f32_e32 v38, v9
	v_mul_f32_e32 v9, 0xbfb8aa3b, v33
	v_exp_f32_e32 v40, v40
	v_exp_f32_e32 v9, v9
	v_rcp_f32_e32 v39, v39
	v_lshl_add_u64 v[24:25], v[14:15], 0, s[0:1]
	v_add_f32_e32 v9, 1.0, v9
	v_pk_mul_f32 v[16:17], v[16:17], v[8:9] op_sel_hi:[1,0]
	v_pk_mul_f32 v[30:31], v[38:39], v[30:31]
	v_lshl_add_u64 v[26:27], v[24:25], 0, v[0:1]
	s_mov_b64 s[0:1], 0xc273000
	s_waitcnt vmcnt(12)
	v_pk_mul_f32 v[20:21], v[172:173], v[28:29]
	v_add_f32_e32 v28, 1.0, v40
	v_rcp_f32_e32 v28, v28
	v_rcp_f32_e32 v29, v9
	v_pk_mul_f32 v[16:17], v[174:175], v[16:17]
	v_pk_mul_f32 v[20:21], v[20:21], v[30:31]
	v_pk_mul_f32 v[22:23], v[28:29], v[32:33]
	s_nop 0
	v_pk_mul_f32 v[16:17], v[16:17], v[22:23]
	v_cvt_pk_bf16_f32 v20, v20, v21
	v_cvt_pk_bf16_f32 v21, v16, v17
	global_store_dwordx2 v[26:27], v[20:21], off
	v_mov_b32_e32 v17, v1
	v_or_b32_e32 v16, 32, v0
	s_waitcnt vmcnt(12)
	v_lshlrev_b32_e32 v26, 16, v208
	v_and_b32_e32 v27, 0xffff0000, v208
	v_lshlrev_b32_e32 v28, 16, v209
	v_and_b32_e32 v29, 0xffff0000, v209
	v_mul_f32_e32 v9, 0xbfb8aa3b, v26
	v_mul_f32_e32 v30, 0xbfb8aa3b, v27
	v_mul_f32_e32 v31, 0xbfb8aa3b, v28
	v_mul_f32_e32 v32, 0xbfb8aa3b, v29
	v_exp_f32_e32 v9, v9
	v_exp_f32_e32 v30, v30
	v_exp_f32_e32 v31, v31
	v_exp_f32_e32 v32, v32
	v_add_f32_e32 v9, 1.0, v9
	v_add_f32_e32 v33, 1.0, v30
	v_add_f32_e32 v34, 1.0, v31
	v_add_f32_e32 v35, 1.0, v32
	v_rcp_f32_e32 v30, v9
	v_rcp_f32_e32 v31, v33
	v_rcp_f32_e32 v32, v34
	v_rcp_f32_e32 v33, v35
	v_pk_mul_f32 v[34:35], v[52:53], v[8:9] op_sel_hi:[1,0]
	v_pk_mul_f32 v[38:39], v[54:55], v[8:9] op_sel_hi:[1,0]
	v_pk_mul_f32 v[26:27], v[30:31], v[26:27]
	v_pk_mul_f32 v[28:29], v[32:33], v[28:29]
	v_lshl_add_u64 v[24:25], v[24:25], 0, v[16:17]
	v_pk_mul_f32 v[30:31], v[44:45], v[8:9] op_sel_hi:[1,0]
	v_pk_mul_f32 v[32:33], v[46:47], v[8:9] op_sel_hi:[1,0]
	s_waitcnt vmcnt(11)
	v_pk_mul_f32 v[20:21], v[176:177], v[34:35]
	v_pk_mul_f32 v[22:23], v[178:179], v[38:39]
	v_pk_mul_f32 v[20:21], v[20:21], v[26:27]
	v_pk_mul_f32 v[22:23], v[22:23], v[28:29]
	v_cvt_pk_bf16_f32 v20, v20, v21
	v_cvt_pk_bf16_f32 v21, v22, v23
	global_store_dwordx2 v[24:25], v[20:21], off
	s_nop 0
	v_lshl_add_u64 v[26:27], v[14:15], 0, s[0:1]
	v_lshl_add_u64 v[28:29], v[26:27], 0, v[0:1]
	s_mov_b64 s[0:1], 0xc373000
	v_lshl_add_u64 v[14:15], v[14:15], 0, s[0:1]
	s_waitcnt vmcnt(11)
	v_lshlrev_b32_e32 v38, 16, v210
	v_and_b32_e32 v39, 0xffff0000, v210
	v_lshlrev_b32_e32 v24, 16, v211
	v_and_b32_e32 v25, 0xffff0000, v211
	v_mul_f32_e32 v9, 0xbfb8aa3b, v38
	v_mul_f32_e32 v40, 0xbfb8aa3b, v39
	v_mul_f32_e32 v41, 0xbfb8aa3b, v24
	v_mul_f32_e32 v42, 0xbfb8aa3b, v25
	v_exp_f32_e32 v9, v9
	v_exp_f32_e32 v40, v40
	v_exp_f32_e32 v41, v41
	v_exp_f32_e32 v42, v42
	v_add_f32_e32 v9, 1.0, v9
	v_add_f32_e32 v43, 1.0, v40
	v_add_f32_e32 v44, 1.0, v41
	v_add_f32_e32 v45, 1.0, v42
	v_rcp_f32_e32 v40, v9
	v_rcp_f32_e32 v41, v43
	v_rcp_f32_e32 v42, v44
	v_rcp_f32_e32 v43, v45
	s_waitcnt vmcnt(10)
	v_pk_mul_f32 v[20:21], v[30:31], v[180:181]
	v_pk_mul_f32 v[22:23], v[32:33], v[182:183]
	v_pk_mul_f32 v[30:31], v[40:41], v[38:39]
	v_pk_mul_f32 v[24:25], v[42:43], v[24:25]
	v_pk_mul_f32 v[20:21], v[20:21], v[30:31]
	v_pk_mul_f32 v[22:23], v[22:23], v[24:25]
	v_cvt_pk_bf16_f32 v20, v20, v21
	v_cvt_pk_bf16_f32 v21, v22, v23
	global_store_dwordx2 v[28:29], v[20:21], off
	v_lshl_add_u64 v[24:25], v[26:27], 0, v[16:17]
	s_waitcnt vmcnt(10)
	v_lshlrev_b32_e32 v26, 16, v212
	v_and_b32_e32 v27, 0xffff0000, v212
	v_lshlrev_b32_e32 v28, 16, v213
	v_and_b32_e32 v29, 0xffff0000, v213
	v_mul_f32_e32 v9, 0xbfb8aa3b, v26
	v_mul_f32_e32 v30, 0xbfb8aa3b, v27
	v_mul_f32_e32 v31, 0xbfb8aa3b, v28
	v_mul_f32_e32 v32, 0xbfb8aa3b, v29
	v_exp_f32_e32 v9, v9
	v_exp_f32_e32 v30, v30
	v_exp_f32_e32 v31, v31
	v_exp_f32_e32 v32, v32
	v_add_f32_e32 v9, 1.0, v9
	v_add_f32_e32 v33, 1.0, v30
	v_add_f32_e32 v34, 1.0, v31
	v_add_f32_e32 v35, 1.0, v32
	v_rcp_f32_e32 v30, v9
	v_rcp_f32_e32 v31, v33
	v_rcp_f32_e32 v32, v34
	v_rcp_f32_e32 v33, v35
	v_pk_mul_f32 v[34:35], v[36:37], v[8:9] op_sel_hi:[1,0]
	v_pk_mul_f32 v[18:19], v[18:19], v[8:9] op_sel_hi:[1,0]
	v_pk_mul_f32 v[26:27], v[30:31], v[26:27]
	v_pk_mul_f32 v[28:29], v[32:33], v[28:29]
	v_pk_mul_f32 v[12:13], v[12:13], v[8:9] op_sel_hi:[1,0]
	v_pk_mul_f32 v[10:11], v[10:11], v[8:9] op_sel_hi:[1,0]
	s_waitcnt vmcnt(9)
	v_pk_mul_f32 v[20:21], v[34:35], v[184:185]
	v_pk_mul_f32 v[18:19], v[18:19], v[186:187]
	v_pk_mul_f32 v[20:21], v[20:21], v[26:27]
	v_pk_mul_f32 v[18:19], v[18:19], v[28:29]
	v_cvt_pk_bf16_f32 v20, v20, v21
	v_cvt_pk_bf16_f32 v21, v18, v19
	global_store_dwordx2 v[24:25], v[20:21], off
	s_nop 0
	v_lshl_add_u64 v[24:25], v[14:15], 0, v[0:1]
	s_waitcnt vmcnt(9)
	v_lshlrev_b32_e32 v26, 16, v214
	v_and_b32_e32 v27, 0xffff0000, v214
	v_lshlrev_b32_e32 v22, 16, v215
	v_and_b32_e32 v23, 0xffff0000, v215
	v_mul_f32_e32 v0, 0xbfb8aa3b, v26
	v_mul_f32_e32 v9, 0xbfb8aa3b, v27
	v_mul_f32_e32 v28, 0xbfb8aa3b, v22
	v_mul_f32_e32 v29, 0xbfb8aa3b, v23
	v_exp_f32_e32 v0, v0
	v_exp_f32_e32 v9, v9
	v_exp_f32_e32 v28, v28
	v_exp_f32_e32 v29, v29
	v_add_f32_e32 v0, 1.0, v0
	v_add_f32_e32 v9, 1.0, v9
	v_add_f32_e32 v30, 1.0, v28
	v_add_f32_e32 v31, 1.0, v29
	v_rcp_f32_e32 v28, v0
	v_rcp_f32_e32 v29, v9
	v_rcp_f32_e32 v30, v30
	v_rcp_f32_e32 v31, v31
	s_waitcnt vmcnt(8)
	v_pk_mul_f32 v[12:13], v[12:13], v[188:189]
	v_pk_mul_f32 v[10:11], v[10:11], v[190:191]
	v_pk_mul_f32 v[18:19], v[28:29], v[26:27]
	v_pk_mul_f32 v[20:21], v[30:31], v[22:23]
	v_pk_mul_f32 v[12:13], v[12:13], v[18:19]
	v_pk_mul_f32 v[10:11], v[10:11], v[20:21]
	v_cvt_pk_bf16_f32 v12, v12, v13
	v_cvt_pk_bf16_f32 v13, v10, v11
	global_store_dwordx2 v[24:25], v[12:13], off
	s_waitcnt vmcnt(8)
	v_lshlrev_b32_e32 v18, 16, v226
	v_and_b32_e32 v19, 0xffff0000, v226
	v_lshlrev_b32_e32 v2, 16, v227
	v_and_b32_e32 v3, 0xffff0000, v227
	v_mul_f32_e32 v0, 0xbfb8aa3b, v18
	v_mul_f32_e32 v9, 0xbfb8aa3b, v19
	v_mul_f32_e32 v20, 0xbfb8aa3b, v2
	v_mul_f32_e32 v21, 0xbfb8aa3b, v3
	v_exp_f32_e32 v0, v0
	v_exp_f32_e32 v9, v9
	v_exp_f32_e32 v20, v20
	v_exp_f32_e32 v21, v21
	v_add_f32_e32 v0, 1.0, v0
	v_add_f32_e32 v9, 1.0, v9
	v_add_f32_e32 v22, 1.0, v20
	v_add_f32_e32 v23, 1.0, v21
	v_rcp_f32_e32 v20, v0
	v_rcp_f32_e32 v21, v9
	v_rcp_f32_e32 v22, v22
	v_rcp_f32_e32 v23, v23
	v_pk_mul_f32 v[6:7], v[6:7], v[8:9] op_sel_hi:[1,0]
	v_pk_mul_f32 v[4:5], v[4:5], v[8:9] op_sel_hi:[1,0]
	v_pk_mul_f32 v[8:9], v[20:21], v[18:19]
	v_pk_mul_f32 v[2:3], v[22:23], v[2:3]
	s_waitcnt vmcnt(7)
	v_pk_mul_f32 v[6:7], v[6:7], v[192:193]
	v_pk_mul_f32 v[4:5], v[4:5], v[194:195]
	v_pk_mul_f32 v[6:7], v[6:7], v[8:9]
	v_pk_mul_f32 v[2:3], v[4:5], v[2:3]
	v_cvt_pk_bf16_f32 v4, v6, v7
	v_cvt_pk_bf16_f32 v5, v2, v3
	v_lshl_add_u64 v[2:3], v[14:15], 0, v[16:17]
	global_store_dwordx2 v[2:3], v[4:5], off
